# v66 plus counted waits: peeled first K iteration of the w_in GEMM skips the 16 queued epilogue stores, and both selection-word loads of a gather chunk in flight together
# baseline (speedup 1.0000x reference)
; #define PG8_STAGE(bufoff, gbase, voff) do { _Pragma("unroll") for (int _i = 0; _i < 2; ++_i) \
;         __builtin_amdgcn_global_load_lds((const unsigned*)((const char*)(gbase) + (voff)[_i]), (PG8_LAS unsigned*)(lds + (bufoff) + ldsw + _i * 8192), 16, 0, 0); } while (0)
; #define PG8_LDA(dst, b, h) do { _Pragma("unroll") for (int m = 0; m < 4; ++m) _Pragma("unroll") for (int k = 0; k < 2; ++k) dst[m][k] = *(const PG8_LAS bf16x8*)(lds + PG8_SA(b, h) + aoff + m * 2048 + k * 1024); } while (0)
; #define PG8_LDB(dst, b, h) do { _Pragma("unroll") for (int n = 0; n < 2; ++n) _Pragma("unroll") for (int k = 0; k < 2; ++k) dst[n][k] = *(const PG8_LAS bf16x8*)(lds + PG8_SB(b, h) + boff + n * 2048 + k * 1024); } while (0)
; #define PG8_MMA(ai, bj, At, Bt) do { __builtin_amdgcn_s_setprio(1); _Pragma("unroll") for (int m = 0; m < 4; ++m) _Pragma("unroll") for (int n = 0; n < 2; ++n) _Pragma("unroll") for (int k = 0; k < 2; ++k) \
;         acc[ai][bj][m][n] = __builtin_amdgcn_mfma_f32_16x16x32_bf16(Bt[n][k], At[m][k], acc[ai][bj][m][n], 0, 0, 0); __builtin_amdgcn_s_setprio(0); } while (0)
; #define PG8_WAIT_V(n) asm volatile("s_waitcnt vmcnt(" #n ")" ::: "memory")
; #define PG8_WAIT_L(n) asm volatile("s_waitcnt lgkmcnt(" #n ")" ::: "memory")
; #define PG8_BAR __builtin_amdgcn_s_barrier()
; #define PG8_SCHED __builtin_amdgcn_sched_barrier(0)
; template <class Epi, class Sched, bool ALIGN_EPI = false, bool SP2 = false>
; __device__ __forceinline__ void gemm_phase(PG8_LAS unsigned char* lds, const Gemm g, const Sched& S, const Epi& E) {
;     ...
;             PG8_LDB(B0, 0, 0); PG8_LDB(B1, 0, 1); PG8_SCHED; PG8_LDA(At, 0, 0); PG8_STAGE(PG8_SA(1, 1), a1 + hstep, voffA);
;             PG8_WAIT_V(8); PG8_WAIT_L(0); PG8_BAR; PG8_MMA(0, 0, At, B0); PG8_MMA(0, 1, At, B1); PG8_BAR; PG8_SCHED;
;     ...
;         if (zero_acc) {
; #pragma unroll
;         for (int a = 0; a < 2; ++a)
; #pragma unroll
;             for (int b = 0; b < 2; ++b)
; #pragma unroll
;                 for (int m = 0; m < 4; ++m)
; #pragma unroll
;                     for (int n = 0; n < 2; ++n) acc[a][b][m][n] = (f32x4){0.f, 0.f, 0.f, 0.f};
;         }
;         cur = nxt; cA = nA; cB = nB; ++ui;
.LBB0_673:
	s_add_u32 s40, s40, 0x80080
	s_addc_u32 s41, s41, 0
	s_add_u32 s35, s42, 0x100
	v_mov_b32_e32 v4, 0
	s_addc_u32 s62, s43, 0
	s_mov_b32 s63, -2
	v_mov_b32_e32 v5, v4
	v_mov_b32_e32 v6, v4
	v_mov_b32_e32 v7, v4
	v_mov_b32_e32 v8, v4
	v_mov_b32_e32 v9, v4
	v_mov_b32_e32 v10, v4
	v_mov_b32_e32 v11, v4
	v_mov_b32_e32 v16, v4
	v_mov_b32_e32 v17, v4
	v_mov_b32_e32 v18, v4
	v_mov_b32_e32 v19, v4
	v_mov_b32_e32 v24, v4
	v_mov_b32_e32 v25, v4
	v_mov_b32_e32 v26, v4
	v_mov_b32_e32 v27, v4
	v_mov_b32_e32 v32, v4
	v_mov_b32_e32 v33, v4
	v_mov_b32_e32 v34, v4
	v_mov_b32_e32 v35, v4
	v_mov_b32_e32 v40, v4
	v_mov_b32_e32 v41, v4
	v_mov_b32_e32 v42, v4
	v_mov_b32_e32 v43, v4
	v_mov_b32_e32 v48, v4
	v_mov_b32_e32 v49, v4
	v_mov_b32_e32 v50, v4
	v_mov_b32_e32 v51, v4
	v_mov_b32_e32 v56, v4
	v_mov_b32_e32 v57, v4
	v_mov_b32_e32 v58, v4
	v_mov_b32_e32 v59, v4
	v_mov_b32_e32 v12, v4
	v_mov_b32_e32 v13, v4
	v_mov_b32_e32 v14, v4
	v_mov_b32_e32 v15, v4
	v_mov_b32_e32 v20, v4
	v_mov_b32_e32 v21, v4
	v_mov_b32_e32 v22, v4
	v_mov_b32_e32 v23, v4
	v_mov_b32_e32 v28, v4
	v_mov_b32_e32 v29, v4
	v_mov_b32_e32 v30, v4
	v_mov_b32_e32 v31, v4
	v_mov_b32_e32 v36, v4
	v_mov_b32_e32 v37, v4
	v_mov_b32_e32 v38, v4
	v_mov_b32_e32 v39, v4
	v_mov_b32_e32 v44, v4
	v_mov_b32_e32 v45, v4
	v_mov_b32_e32 v46, v4
	v_mov_b32_e32 v47, v4
	v_mov_b32_e32 v52, v4
	v_mov_b32_e32 v53, v4
	v_mov_b32_e32 v54, v4
	v_mov_b32_e32 v55, v4
	v_mov_b32_e32 v60, v4
	v_mov_b32_e32 v61, v4
	v_mov_b32_e32 v62, v4
	v_mov_b32_e32 v63, v4
	v_mov_b32_e32 v64, v4
	v_mov_b32_e32 v65, v4
	v_mov_b32_e32 v66, v4
	v_mov_b32_e32 v67, v4
	v_mov_b32_e32 v68, v4
	v_mov_b32_e32 v69, v4
	v_mov_b32_e32 v70, v4
	v_mov_b32_e32 v71, v4
	v_mov_b32_e32 v72, v4
	v_mov_b32_e32 v73, v4
	v_mov_b32_e32 v74, v4
	v_mov_b32_e32 v75, v4
	v_mov_b32_e32 v80, v4
	v_mov_b32_e32 v81, v4
	v_mov_b32_e32 v82, v4
	v_mov_b32_e32 v83, v4
	v_mov_b32_e32 v88, v4
	v_mov_b32_e32 v89, v4
	v_mov_b32_e32 v90, v4
	v_mov_b32_e32 v91, v4
	v_mov_b32_e32 v96, v4
	v_mov_b32_e32 v97, v4
	v_mov_b32_e32 v98, v4
	v_mov_b32_e32 v99, v4
	v_mov_b32_e32 v104, v4
	v_mov_b32_e32 v105, v4
	v_mov_b32_e32 v106, v4
	v_mov_b32_e32 v107, v4
	v_mov_b32_e32 v112, v4
	v_mov_b32_e32 v113, v4
	v_mov_b32_e32 v114, v4
	v_mov_b32_e32 v115, v4
	v_mov_b32_e32 v120, v4
	v_mov_b32_e32 v121, v4
	v_mov_b32_e32 v122, v4
	v_mov_b32_e32 v123, v4
	v_mov_b32_e32 v76, v4
	v_mov_b32_e32 v77, v4
	v_mov_b32_e32 v78, v4
	v_mov_b32_e32 v79, v4
	v_mov_b32_e32 v84, v4
	v_mov_b32_e32 v85, v4
	v_mov_b32_e32 v86, v4
	v_mov_b32_e32 v87, v4
	v_mov_b32_e32 v92, v4
	v_mov_b32_e32 v93, v4
	v_mov_b32_e32 v94, v4
	v_mov_b32_e32 v95, v4
	v_mov_b32_e32 v100, v4
	v_mov_b32_e32 v101, v4
	v_mov_b32_e32 v102, v4
	v_mov_b32_e32 v103, v4
	v_mov_b32_e32 v108, v4
	v_mov_b32_e32 v109, v4
	v_mov_b32_e32 v110, v4
	v_mov_b32_e32 v111, v4
	v_mov_b32_e32 v116, v4
	v_mov_b32_e32 v117, v4
	v_mov_b32_e32 v118, v4
	v_mov_b32_e32 v119, v4
	v_mov_b32_e32 v124, v4
	v_mov_b32_e32 v125, v4
	v_mov_b32_e32 v126, v4
	v_mov_b32_e32 v127, v4
	v_mov_b32_e32 v128, v4
	v_mov_b32_e32 v129, v4
	v_mov_b32_e32 v130, v4
	v_mov_b32_e32 v131, v4
	v_add_u32_e32 v249, 0x10000, v173
	s_cmp_eq_u32 s32, 0
	s_cbranch_scc1 .LBB0_674
	s_add_u32 s42, s40, 0xfff80080
	s_addc_u32 s43, s41, -1
	s_add_i32 s64, 0, 0x10000
	s_cmp_eq_u32 s63, 28
	s_cselect_b32 s45, s5, s43
	s_cselect_b32 s44, s4, s42
	s_cselect_b32 s43, s37, s62
	s_cselect_b32 s42, s36, s35
	s_add_i32 s66, 0, 0x14000
	ds_read_b128 v[132:135], v249
	ds_read_b128 v[136:139], v249 offset:1024
	ds_read_b128 v[140:143], v249 offset:2048
	ds_read_b128 v[144:147], v249 offset:3072
	ds_read_b128 v[158:161], v249 offset:16384
	ds_read_b128 v[174:177], v249 offset:17408
	ds_read_b128 v[206:209], v249 offset:18432
	ds_read_b128 v[210:213], v249 offset:19456
	s_add_i32 m0, s39, 0xc000
	ds_read_b128 v[214:217], v204
	ds_read_b128 v[218:221], v204 offset:1024
	ds_read_b128 v[222:225], v204 offset:2048
	ds_read_b128 v[226:229], v204 offset:3072
	ds_read_b128 v[230:233], v204 offset:4096
	ds_read_b128 v[234:237], v204 offset:5120
	ds_read_b128 v[238:241], v204 offset:6144
	ds_read_b128 v[242:245], v204 offset:7168
	global_load_lds_dwordx4 v154, s[40:41]
	s_add_i32 m0, s39, 0xe000
	s_nop 0
	global_load_lds_dwordx4 v156, s[40:41]
	s_waitcnt vmcnt(24) lgkmcnt(0)
	s_setprio 0
	s_barrier
	v_mfma_f32_16x16x32_bf16 v[128:131], v[132:135], v[214:217], v[128:131]
	v_mfma_f32_16x16x32_bf16 v[124:127], v[140:143], v[214:217], v[124:127]
	v_mfma_f32_16x16x32_bf16 v[116:119], v[132:135], v[222:225], v[116:119]
	v_mfma_f32_16x16x32_bf16 v[108:111], v[140:143], v[222:225], v[108:111]
	v_mfma_f32_16x16x32_bf16 v[100:103], v[132:135], v[230:233], v[100:103]
	v_mfma_f32_16x16x32_bf16 v[92:95], v[140:143], v[230:233], v[92:95]
	v_mfma_f32_16x16x32_bf16 v[84:87], v[132:135], v[238:241], v[84:87]
	v_mfma_f32_16x16x32_bf16 v[76:79], v[140:143], v[238:241], v[76:79]
	v_mfma_f32_16x16x32_bf16 v[128:131], v[136:139], v[218:221], v[128:131]
	v_mfma_f32_16x16x32_bf16 v[124:127], v[144:147], v[218:221], v[124:127]
	v_mfma_f32_16x16x32_bf16 v[116:119], v[136:139], v[226:229], v[116:119]
	v_mfma_f32_16x16x32_bf16 v[108:111], v[144:147], v[226:229], v[108:111]
	v_mfma_f32_16x16x32_bf16 v[100:103], v[136:139], v[234:237], v[100:103]
	v_mfma_f32_16x16x32_bf16 v[92:95], v[144:147], v[234:237], v[92:95]
	v_mfma_f32_16x16x32_bf16 v[84:87], v[136:139], v[242:245], v[84:87]
	v_mfma_f32_16x16x32_bf16 v[76:79], v[144:147], v[242:245], v[76:79]
	v_mfma_f32_16x16x32_bf16 v[120:123], v[158:161], v[214:217], v[120:123]
	v_mfma_f32_16x16x32_bf16 v[112:115], v[206:209], v[214:217], v[112:115]
	v_mfma_f32_16x16x32_bf16 v[104:107], v[158:161], v[222:225], v[104:107]
	v_mfma_f32_16x16x32_bf16 v[96:99], v[206:209], v[222:225], v[96:99]
	v_mfma_f32_16x16x32_bf16 v[88:91], v[158:161], v[230:233], v[88:91]
	v_mfma_f32_16x16x32_bf16 v[80:83], v[206:209], v[230:233], v[80:83]
	v_mfma_f32_16x16x32_bf16 v[72:75], v[158:161], v[238:241], v[72:75]
	v_mfma_f32_16x16x32_bf16 v[68:71], v[206:209], v[238:241], v[68:71]
	v_mfma_f32_16x16x32_bf16 v[120:123], v[174:177], v[218:221], v[120:123]
	v_mfma_f32_16x16x32_bf16 v[112:115], v[210:213], v[218:221], v[112:115]
	v_mfma_f32_16x16x32_bf16 v[104:107], v[174:177], v[226:229], v[104:107]
	v_mfma_f32_16x16x32_bf16 v[96:99], v[210:213], v[226:229], v[96:99]
	v_mfma_f32_16x16x32_bf16 v[88:91], v[174:177], v[234:237], v[88:91]
	v_mfma_f32_16x16x32_bf16 v[80:83], v[210:213], v[234:237], v[80:83]
	v_mfma_f32_16x16x32_bf16 v[72:75], v[174:177], v[242:245], v[72:75]
	v_mfma_f32_16x16x32_bf16 v[68:71], v[210:213], v[242:245], v[68:71]
	s_setprio 3
	s_barrier
; #define PG8_STAGE(bufoff, gbase, voff) do { _Pragma("unroll") for (int _i = 0; _i < 2; ++_i) \
;         __builtin_amdgcn_global_load_lds((const unsigned*)((const char*)(gbase) + (voff)[_i]), (PG8_LAS unsigned*)(lds + (bufoff) + ldsw + _i * 8192), 16, 0, 0); } while (0)
; #define PG8_LDA(dst, b, h) do { _Pragma("unroll") for (int m = 0; m < 4; ++m) _Pragma("unroll") for (int k = 0; k < 2; ++k) dst[m][k] = *(const PG8_LAS bf16x8*)(lds + PG8_SA(b, h) + aoff + m * 2048 + k * 1024); } while (0)
; #define PG8_LDB(dst, b, h) do { _Pragma("unroll") for (int n = 0; n < 2; ++n) _Pragma("unroll") for (int k = 0; k < 2; ++k) dst[n][k] = *(const PG8_LAS bf16x8*)(lds + PG8_SB(b, h) + boff + n * 2048 + k * 1024); } while (0)
; #define PG8_MMA(ai, bj, At, Bt) do { __builtin_amdgcn_s_setprio(1); _Pragma("unroll") for (int m = 0; m < 4; ++m) _Pragma("unroll") for (int n = 0; n < 2; ++n) _Pragma("unroll") for (int k = 0; k < 2; ++k) \
;         acc[ai][bj][m][n] = __builtin_amdgcn_mfma_f32_16x16x32_bf16(Bt[n][k], At[m][k], acc[ai][bj][m][n], 0, 0, 0); __builtin_amdgcn_s_setprio(0); } while (0)
; #define PG8_WAIT_V(n) asm volatile("s_waitcnt vmcnt(" #n ")" ::: "memory")
; #define PG8_WAIT_L(n) asm volatile("s_waitcnt lgkmcnt(" #n ")" ::: "memory")
; #define PG8_BAR __builtin_amdgcn_s_barrier()
; #define PG8_SCHED __builtin_amdgcn_sched_barrier(0)
; template <class Epi, class Sched, bool ALIGN_EPI = false, bool SP2 = false>
; __device__ __forceinline__ void gemm_phase(PG8_LAS unsigned char* lds, const Gemm g, const Sched& S, const Epi& E) {
;     ...
;             PG8_WAIT_V(8); PG8_WAIT_L(0); PG8_BAR; PG8_MMA(0, 0, At, B0); PG8_MMA(0, 1, At, B1); PG8_BAR; PG8_SCHED;
;             PG8_LDA(At, 0, 1); PG8_STAGE(PG8_SB(0, 0), b2, voffB); PG8_STAGE(PG8_SB(0, 1), b2 + hstep, voffB); PG8_STAGE(PG8_SA(0, 0), a2, voffA);
;             PG8_WAIT_V(8); PG8_WAIT_L(0); PG8_BAR; PG8_MMA(1, 0, At, B0); PG8_MMA(1, 1, At, B1); PG8_BAR; PG8_SCHED;
;             PG8_LDB(B0, 1, 0); PG8_LDB(B1, 1, 1); PG8_SCHED; PG8_LDA(At, 1, 0); PG8_STAGE(PG8_SA(0, 1), a2 + hstep, voffA);
;             PG8_WAIT_V(8); PG8_WAIT_L(0); PG8_BAR; PG8_MMA(0, 0, At, B0); PG8_MMA(0, 1, At, B1); PG8_BAR; PG8_SCHED;
	s_add_i32 s64, s64, s46
	s_mov_b32 m0, s64
	ds_read_b128 v[214:217], v204 offset:16384
	ds_read_b128 v[218:221], v204 offset:17408
	ds_read_b128 v[222:225], v204 offset:18432
	ds_read_b128 v[226:229], v204 offset:19456
	ds_read_b128 v[230:233], v204 offset:20480
	ds_read_b128 v[234:237], v204 offset:21504
	ds_read_b128 v[238:241], v204 offset:22528
	ds_read_b128 v[242:245], v204 offset:23552
	global_load_lds_dwordx4 v2, s[42:43]
	s_add_i32 m0, s64, 0x2000
	s_add_u32 s64, s42, 0x80000
	s_addc_u32 s65, s43, 0
	s_add_i32 s66, s66, s46
	global_load_lds_dwordx4 v148, s[42:43]
	s_mov_b32 m0, s66
	s_nop 0
	global_load_lds_dwordx4 v2, s[64:65]
	s_add_i32 m0, s66, 0x2000
	s_nop 0
	global_load_lds_dwordx4 v148, s[64:65]
	s_mov_b32 m0, s39
	s_nop 0
	global_load_lds_dwordx4 v152, s[44:45]
	s_mov_b32 m0, s51
	s_nop 0
	global_load_lds_dwordx4 v150, s[44:45]
	s_waitcnt vmcnt(24) lgkmcnt(0)
	s_setprio 0
	s_barrier
	v_mfma_f32_16x16x32_bf16 v[64:67], v[132:135], v[214:217], v[64:67]
	v_mfma_f32_16x16x32_bf16 v[60:63], v[140:143], v[214:217], v[60:63]
	v_mfma_f32_16x16x32_bf16 v[52:55], v[132:135], v[222:225], v[52:55]
	v_mfma_f32_16x16x32_bf16 v[44:47], v[140:143], v[222:225], v[44:47]
	v_mfma_f32_16x16x32_bf16 v[36:39], v[132:135], v[230:233], v[36:39]
	v_mfma_f32_16x16x32_bf16 v[28:31], v[140:143], v[230:233], v[28:31]
	v_mfma_f32_16x16x32_bf16 v[20:23], v[132:135], v[238:241], v[20:23]
	v_mfma_f32_16x16x32_bf16 v[12:15], v[140:143], v[238:241], v[12:15]
	v_mfma_f32_16x16x32_bf16 v[64:67], v[136:139], v[218:221], v[64:67]
	v_mfma_f32_16x16x32_bf16 v[60:63], v[144:147], v[218:221], v[60:63]
	v_mfma_f32_16x16x32_bf16 v[52:55], v[136:139], v[226:229], v[52:55]
	v_mfma_f32_16x16x32_bf16 v[44:47], v[144:147], v[226:229], v[44:47]
	v_mfma_f32_16x16x32_bf16 v[36:39], v[136:139], v[234:237], v[36:39]
	v_mfma_f32_16x16x32_bf16 v[28:31], v[144:147], v[234:237], v[28:31]
	v_mfma_f32_16x16x32_bf16 v[20:23], v[136:139], v[242:245], v[20:23]
	v_mfma_f32_16x16x32_bf16 v[12:15], v[144:147], v[242:245], v[12:15]
	v_mfma_f32_16x16x32_bf16 v[56:59], v[158:161], v[214:217], v[56:59]
	v_mfma_f32_16x16x32_bf16 v[48:51], v[206:209], v[214:217], v[48:51]
	v_mfma_f32_16x16x32_bf16 v[40:43], v[158:161], v[222:225], v[40:43]
	v_mfma_f32_16x16x32_bf16 v[32:35], v[206:209], v[222:225], v[32:35]
	v_mfma_f32_16x16x32_bf16 v[24:27], v[158:161], v[230:233], v[24:27]
	v_mfma_f32_16x16x32_bf16 v[16:19], v[206:209], v[230:233], v[16:19]
	v_mfma_f32_16x16x32_bf16 v[8:11], v[158:161], v[238:241], v[8:11]
	v_mfma_f32_16x16x32_bf16 v[4:7], v[206:209], v[238:241], v[4:7]
	v_mfma_f32_16x16x32_bf16 v[56:59], v[174:177], v[218:221], v[56:59]
	v_mfma_f32_16x16x32_bf16 v[48:51], v[210:213], v[218:221], v[48:51]
	v_mfma_f32_16x16x32_bf16 v[40:43], v[174:177], v[226:229], v[40:43]
	v_mfma_f32_16x16x32_bf16 v[32:35], v[210:213], v[226:229], v[32:35]
	v_mfma_f32_16x16x32_bf16 v[24:27], v[174:177], v[234:237], v[24:27]
	v_mfma_f32_16x16x32_bf16 v[16:19], v[210:213], v[234:237], v[16:19]
	v_mfma_f32_16x16x32_bf16 v[8:11], v[174:177], v[242:245], v[8:11]
	v_mfma_f32_16x16x32_bf16 v[4:7], v[210:213], v[242:245], v[4:7]
	s_setprio 3
	s_barrier
	s_add_i32 s64, 0, 0x18000
	s_add_i32 s65, 0, 0x1c000
	ds_read_b128 v[132:135], v249 offset:32768
	ds_read_b128 v[136:139], v249 offset:33792
	ds_read_b128 v[140:143], v249 offset:34816
	ds_read_b128 v[144:147], v249 offset:35840
	ds_read_b128 v[158:161], v249 offset:49152
	ds_read_b128 v[174:177], v249 offset:50176
	ds_read_b128 v[206:209], v249 offset:51200
	ds_read_b128 v[210:213], v249 offset:52224
	s_add_u32 s100, s44, 0x80
	s_addc_u32 s101, s45, 0
	s_add_u32 s44, s44, 0x80000
	s_addc_u32 s45, s45, 0
	s_mov_b32 m0, s52
	ds_read_b128 v[214:217], v204 offset:32768
	ds_read_b128 v[218:221], v204 offset:33792
	ds_read_b128 v[222:225], v204 offset:34816
	ds_read_b128 v[226:229], v204 offset:35840
	ds_read_b128 v[230:233], v204 offset:36864
	ds_read_b128 v[234:237], v204 offset:37888
	ds_read_b128 v[238:241], v204 offset:38912
	ds_read_b128 v[242:245], v204 offset:39936
	global_load_lds_dwordx4 v152, s[44:45]
	s_mov_b32 m0, s53
	s_nop 0
	global_load_lds_dwordx4 v150, s[44:45]
	s_waitcnt vmcnt(8) lgkmcnt(0)
	s_setprio 0
	s_barrier
; #define PG8_STAGE(bufoff, gbase, voff) do { _Pragma("unroll") for (int _i = 0; _i < 2; ++_i) \
;         __builtin_amdgcn_global_load_lds((const unsigned*)((const char*)(gbase) + (voff)[_i]), (PG8_LAS unsigned*)(lds + (bufoff) + ldsw + _i * 8192), 16, 0, 0); } while (0)
; #define PG8_LDA(dst, b, h) do { _Pragma("unroll") for (int m = 0; m < 4; ++m) _Pragma("unroll") for (int k = 0; k < 2; ++k) dst[m][k] = *(const PG8_LAS bf16x8*)(lds + PG8_SA(b, h) + aoff + m * 2048 + k * 1024); } while (0)
; #define PG8_LDB(dst, b, h) do { _Pragma("unroll") for (int n = 0; n < 2; ++n) _Pragma("unroll") for (int k = 0; k < 2; ++k) dst[n][k] = *(const PG8_LAS bf16x8*)(lds + PG8_SB(b, h) + boff + n * 2048 + k * 1024); } while (0)
; #define PG8_MMA(ai, bj, At, Bt) do { __builtin_amdgcn_s_setprio(1); _Pragma("unroll") for (int m = 0; m < 4; ++m) _Pragma("unroll") for (int n = 0; n < 2; ++n) _Pragma("unroll") for (int k = 0; k < 2; ++k) \
;         acc[ai][bj][m][n] = __builtin_amdgcn_mfma_f32_16x16x32_bf16(Bt[n][k], At[m][k], acc[ai][bj][m][n], 0, 0, 0); __builtin_amdgcn_s_setprio(0); } while (0)
; #define PG8_WAIT_V(n) asm volatile("s_waitcnt vmcnt(" #n ")" ::: "memory")
; #define PG8_WAIT_L(n) asm volatile("s_waitcnt lgkmcnt(" #n ")" ::: "memory")
; #define PG8_BAR __builtin_amdgcn_s_barrier()
; #define PG8_SCHED __builtin_amdgcn_sched_barrier(0)
; template <class Epi, class Sched, bool ALIGN_EPI = false, bool SP2 = false>
; __device__ __forceinline__ void gemm_phase(PG8_LAS unsigned char* lds, const Gemm g, const Sched& S, const Epi& E) {
;     ...
;             PG8_LDB(B0, 1, 0); PG8_LDB(B1, 1, 1); PG8_SCHED; PG8_LDA(At, 1, 0); PG8_STAGE(PG8_SA(0, 1), a2 + hstep, voffA);
;             PG8_WAIT_V(8); PG8_WAIT_L(0); PG8_BAR; PG8_MMA(0, 0, At, B0); PG8_MMA(0, 1, At, B1); PG8_BAR; PG8_SCHED;
;             PG8_LDA(At, 1, 1); PG8_STAGE(PG8_SB(1, 0), b3, voffB); PG8_STAGE(PG8_SB(1, 1), b3 + hstep, voffB); PG8_STAGE(PG8_SA(1, 0), a3, voffA);
;             PG8_WAIT_V(8); PG8_WAIT_L(0); PG8_BAR; PG8_MMA(1, 0, At, B0); PG8_MMA(1, 1, At, B1); PG8_BAR; PG8_SCHED;
	v_mfma_f32_16x16x32_bf16 v[128:131], v[132:135], v[214:217], v[128:131]
	v_mfma_f32_16x16x32_bf16 v[124:127], v[140:143], v[214:217], v[124:127]
	v_mfma_f32_16x16x32_bf16 v[116:119], v[132:135], v[222:225], v[116:119]
	v_mfma_f32_16x16x32_bf16 v[108:111], v[140:143], v[222:225], v[108:111]
	v_mfma_f32_16x16x32_bf16 v[100:103], v[132:135], v[230:233], v[100:103]
	v_mfma_f32_16x16x32_bf16 v[92:95], v[140:143], v[230:233], v[92:95]
	v_mfma_f32_16x16x32_bf16 v[84:87], v[132:135], v[238:241], v[84:87]
	v_mfma_f32_16x16x32_bf16 v[76:79], v[140:143], v[238:241], v[76:79]
	v_mfma_f32_16x16x32_bf16 v[128:131], v[136:139], v[218:221], v[128:131]
	v_mfma_f32_16x16x32_bf16 v[124:127], v[144:147], v[218:221], v[124:127]
	v_mfma_f32_16x16x32_bf16 v[116:119], v[136:139], v[226:229], v[116:119]
	v_mfma_f32_16x16x32_bf16 v[108:111], v[144:147], v[226:229], v[108:111]
	v_mfma_f32_16x16x32_bf16 v[100:103], v[136:139], v[234:237], v[100:103]
	v_mfma_f32_16x16x32_bf16 v[92:95], v[144:147], v[234:237], v[92:95]
	v_mfma_f32_16x16x32_bf16 v[84:87], v[136:139], v[242:245], v[84:87]
	v_mfma_f32_16x16x32_bf16 v[76:79], v[144:147], v[242:245], v[76:79]
	v_mfma_f32_16x16x32_bf16 v[120:123], v[158:161], v[214:217], v[120:123]
	v_mfma_f32_16x16x32_bf16 v[112:115], v[206:209], v[214:217], v[112:115]
	v_mfma_f32_16x16x32_bf16 v[104:107], v[158:161], v[222:225], v[104:107]
	v_mfma_f32_16x16x32_bf16 v[96:99], v[206:209], v[222:225], v[96:99]
	v_mfma_f32_16x16x32_bf16 v[88:91], v[158:161], v[230:233], v[88:91]
	v_mfma_f32_16x16x32_bf16 v[80:83], v[206:209], v[230:233], v[80:83]
	v_mfma_f32_16x16x32_bf16 v[72:75], v[158:161], v[238:241], v[72:75]
	v_mfma_f32_16x16x32_bf16 v[68:71], v[206:209], v[238:241], v[68:71]
	v_mfma_f32_16x16x32_bf16 v[120:123], v[174:177], v[218:221], v[120:123]
	v_mfma_f32_16x16x32_bf16 v[112:115], v[210:213], v[218:221], v[112:115]
	v_mfma_f32_16x16x32_bf16 v[104:107], v[174:177], v[226:229], v[104:107]
	v_mfma_f32_16x16x32_bf16 v[96:99], v[210:213], v[226:229], v[96:99]
	v_mfma_f32_16x16x32_bf16 v[88:91], v[174:177], v[234:237], v[88:91]
	v_mfma_f32_16x16x32_bf16 v[80:83], v[210:213], v[234:237], v[80:83]
	v_mfma_f32_16x16x32_bf16 v[72:75], v[174:177], v[242:245], v[72:75]
	v_mfma_f32_16x16x32_bf16 v[68:71], v[210:213], v[242:245], v[68:71]
	s_setprio 3
	s_barrier
	s_add_i32 s44, s64, s46
	s_add_i32 m0, s44, 0xffffff80
	ds_read_b128 v[214:217], v204 offset:49152
	ds_read_b128 v[218:221], v204 offset:50176
	ds_read_b128 v[222:225], v204 offset:51200
	ds_read_b128 v[226:229], v204 offset:52224
	ds_read_b128 v[230:233], v204 offset:53248
	ds_read_b128 v[234:237], v204 offset:54272
	ds_read_b128 v[238:241], v204 offset:55296
	ds_read_b128 v[242:245], v204 offset:56320
	global_load_lds_dwordx4 v2, s[42:43] offset:128
	s_add_i32 m0, s44, 0x1f80
	s_add_i32 s44, s65, s46
	global_load_lds_dwordx4 v148, s[42:43] offset:128
	s_add_u32 s42, s42, 0x80080
	s_addc_u32 s43, s43, 0
	s_mov_b32 m0, s44
	s_nop 0
	global_load_lds_dwordx4 v2, s[42:43]
	s_add_i32 m0, s44, 0x2000
	s_nop 0
	global_load_lds_dwordx4 v148, s[42:43]
	s_mov_b32 m0, s54
	s_nop 0
	global_load_lds_dwordx4 v152, s[100:101]
	s_mov_b32 m0, s55
	s_nop 0
	global_load_lds_dwordx4 v150, s[100:101]
	s_waitcnt vmcnt(8) lgkmcnt(0)
	s_setprio 0
	s_barrier
	v_mfma_f32_16x16x32_bf16 v[64:67], v[132:135], v[214:217], v[64:67]
	v_mfma_f32_16x16x32_bf16 v[60:63], v[140:143], v[214:217], v[60:63]
	v_mfma_f32_16x16x32_bf16 v[52:55], v[132:135], v[222:225], v[52:55]
	v_mfma_f32_16x16x32_bf16 v[44:47], v[140:143], v[222:225], v[44:47]
	v_mfma_f32_16x16x32_bf16 v[36:39], v[132:135], v[230:233], v[36:39]
	v_mfma_f32_16x16x32_bf16 v[28:31], v[140:143], v[230:233], v[28:31]
	v_mfma_f32_16x16x32_bf16 v[20:23], v[132:135], v[238:241], v[20:23]
	v_mfma_f32_16x16x32_bf16 v[12:15], v[140:143], v[238:241], v[12:15]
	v_mfma_f32_16x16x32_bf16 v[64:67], v[136:139], v[218:221], v[64:67]
	v_mfma_f32_16x16x32_bf16 v[60:63], v[144:147], v[218:221], v[60:63]
	v_mfma_f32_16x16x32_bf16 v[52:55], v[136:139], v[226:229], v[52:55]
	v_mfma_f32_16x16x32_bf16 v[44:47], v[144:147], v[226:229], v[44:47]
	v_mfma_f32_16x16x32_bf16 v[36:39], v[136:139], v[234:237], v[36:39]
	v_mfma_f32_16x16x32_bf16 v[28:31], v[144:147], v[234:237], v[28:31]
	v_mfma_f32_16x16x32_bf16 v[20:23], v[136:139], v[242:245], v[20:23]
	v_mfma_f32_16x16x32_bf16 v[12:15], v[144:147], v[242:245], v[12:15]
	v_mfma_f32_16x16x32_bf16 v[56:59], v[158:161], v[214:217], v[56:59]
	v_mfma_f32_16x16x32_bf16 v[48:51], v[206:209], v[214:217], v[48:51]
	v_mfma_f32_16x16x32_bf16 v[40:43], v[158:161], v[222:225], v[40:43]
	v_mfma_f32_16x16x32_bf16 v[32:35], v[206:209], v[222:225], v[32:35]
	v_mfma_f32_16x16x32_bf16 v[24:27], v[158:161], v[230:233], v[24:27]
	v_mfma_f32_16x16x32_bf16 v[16:19], v[206:209], v[230:233], v[16:19]
	v_mfma_f32_16x16x32_bf16 v[8:11], v[158:161], v[238:241], v[8:11]
	v_mfma_f32_16x16x32_bf16 v[4:7], v[206:209], v[238:241], v[4:7]
	v_mfma_f32_16x16x32_bf16 v[56:59], v[174:177], v[218:221], v[56:59]
	v_mfma_f32_16x16x32_bf16 v[48:51], v[210:213], v[218:221], v[48:51]
	v_mfma_f32_16x16x32_bf16 v[40:43], v[174:177], v[226:229], v[40:43]
	v_mfma_f32_16x16x32_bf16 v[32:35], v[210:213], v[226:229], v[32:35]
	v_mfma_f32_16x16x32_bf16 v[24:27], v[174:177], v[234:237], v[24:27]
	v_mfma_f32_16x16x32_bf16 v[16:19], v[210:213], v[234:237], v[16:19]
	v_mfma_f32_16x16x32_bf16 v[8:11], v[174:177], v[242:245], v[8:11]
	v_mfma_f32_16x16x32_bf16 v[4:7], v[210:213], v[242:245], v[4:7]
	s_setprio 3
	s_barrier
	s_add_i32 s63, s63, 2
	s_add_u32 s40, s40, 0x100
	s_addc_u32 s41, s41, 0
	s_add_u32 s35, s35, 0x100
	s_addc_u32 s62, s62, 0
	s_cmp_gt_u32 s63, 29
	s_cbranch_scc0 .LBB0_674
	s_branch .Lpost_p4
	.p2align 6
	s_nop 0
